# G3 start de-phasing shortened to 0/2/4/6 us
# baseline (speedup 1.0000x reference)
.LBB0_366:
	s_cmp_lt_i32 s56, 5
	s_cselect_b64 s[0:1], -1, 0
	s_and_b64 s[8:9], s[0:1], s[4:5]
	s_andn2_b64 vcc, exec, s[8:9]
	s_cbranch_vccnz .LBB0_408
	s_bfe_u32 s0, s2, 0x20003
	s_cmp_eq_u32 s0, 0
	v_mbcnt_lo_u32_b32 v0, -1, 0
	v_mbcnt_hi_u32_b32 v0, -1, v0
	s_cbranch_scc1 .LBB0_370
	s_mul_i32 s0, s0, 1
